# static s_setprio 1 for waves 4-7 also over the mem_attn phase
# baseline (speedup 1.0000x reference)
; #define LAS __attribute__((address_space(3)))
; __device__ __forceinline__ int opaque_tid(int wv) { int t = wv * 64 + (int)__builtin_amdgcn_mbcnt_hi(~0u, __builtin_amdgcn_mbcnt_lo(~0u, 0u)); asm volatile("" : "+v"(t)); return t; }
; __device__ __forceinline__ void mem_attn_phase(int wv, const Args& A, LAS unsigned char* lds, int G) {
;     const int tid = opaque_tid(wv), lane = tid & 63, w = tid >> 6, fr = lane & 15, fq = lane >> 4;
;     unsigned char* ws = A.ws;
;     const h16* MQ = (const h16*)(ws + WS_MQ); h16* MO = (h16*)(ws + WS_MO);
;     LAS h16* Pw = (LAS h16*)(lds + w * 8448);
;     for (int wu = blockIdx.x * 8 + w; wu < (MT / 16) * 4; wu += G * 8) {
;         const int blk = wu >> 3; const int h = blk & 3, tile = (blk >> 2) * 8 + (wu & 7); const size_t row0 = (size_t)tile * 16;
;         const h16* Kb; const h16* VTb;
;         if (row0 < NP) { const int b = (int)(row0 >> 14); Kb = (const h16*)(ws + WS_MK16) + (size_t)b * 256 * 512; VTb = (const h16*)(ws + WS_MVT) + (size_t)(b * 4 + h) * 32768; }
;         else { const int bs = (int)((row0 - NP) >> 6); Kb = (const h16*)(ws + WS_CMK) + (size_t)bs * 256 * 512; VTb = (const h16*)(ws + WS_CMVT) + (size_t)(bs * 4 + h) * 32768; }
;         h16x8 qf[4];
; #pragma unroll
;         for (int ks = 0; ks < 4; ++ks) qf[ks] = __builtin_bit_cast(h16x8, *(const u32x4*)(MQ + (row0 + fr) * 512 + h * 128 + ks * 32 + fq * 8));
.LBB0_2399:
	s_or_b64 exec, exec, s[6:7]
	s_waitcnt lgkmcnt(0)
	v_mov_b32_e32 v0, v170
	s_barrier
	v_mbcnt_lo_u32_b32 v0, -1, 0
	v_mbcnt_hi_u32_b32 v0, -1, v0
	v_and_b32_e32 v1, 15, v0
	v_lshrrev_b32_e32 v2, 4, v0
	v_ashrrev_i32_e32 v64, 6, v170
	s_nop 0
	v_readfirstlane_b32 s70, v64
	v_lshlrev_b32_e32 v4, 10, v1
	v_lshl_add_u32 v4, v2, 4, v4
	v_lshlrev_b32_e32 v5, 9, v1
	v_lshl_add_u32 v5, v2, 4, v5
	v_lshlrev_b32_e32 v7, 4, v0
	v_add_u32_e32 v7, 0x11000, v7
	s_lshl_b32 s32, s70, 13
	v_add_u32_e32 v6, s32, v7
	s_mul_i32 s32, s70, 0x2100
	v_mul_u32_u24_e32 v8, 0x210, v1
	v_add_u32_e32 v8, s32, v8
	v_lshl_add_u32 v9, v2, 4, v8
	v_lshl_add_u32 v8, v2, 3, v8
	v_lshlrev_b32_e32 v10, 10, v1
	v_lshl_add_u32 v10, v2, 3, v10
	v_xor_b32_e32 v11, 16, v0
	v_lshlrev_b32_e32 v11, 2, v11
	v_xor_b32_e32 v12, 32, v0
	v_lshlrev_b32_e32 v12, 2, v12
	s_cmp_ge_u32 s70, 4
	s_cbranch_scc0 .Lma_prio_done
	s_setprio 1
.Lma_prio_done:
	s_mov_b32 s71, 0
	s_lshl_b32 s72, s71, 8
	s_add_i32 s73, s2, s72
	s_and_b32 s74, s73, 3
	s_lshr_b32 s75, s73, 2
	s_lshl_b32 s75, s75, 3
	s_add_i32 s75, s75, s70
	s_lshr_b32 s76, s75, 10
	s_lshl_b32 s32, s76, 18
	s_lshl_b32 s33, s74, 8
	s_add_i32 s32, s32, s33
	s_lshl_b32 s33, s70, 15
	s_add_i32 s32, s32, s33
	s_add_u32 s78, s44, 0x3cc4d000
	s_addc_u32 s79, s45, 0
	s_add_u32 s78, s78, s32
	s_addc_u32 s79, s79, 0
	s_add_u32 s88, s78, 0x4000
	s_addc_u32 s89, s79, 0
	s_lshl_b32 s32, s76, 2
	s_add_i32 s32, s32, s74
	s_lshl_b32 s32, s32, 16
	s_lshl_b32 s33, s70, 13
	s_add_i32 s32, s32, s33
	s_add_u32 s90, s44, 0x3cccd000
	s_addc_u32 s91, s45, 0
	s_add_u32 s90, s90, s32
	s_addc_u32 s91, s91, 0
	s_lshl_b32 s32, s75, 14
	s_lshl_b32 s33, s74, 8
	s_add_i32 s32, s32, s33
	s_add_u32 s92, s44, 0x324c1000
	s_addc_u32 s93, s45, 0
	s_add_u32 s92, s92, s32
	s_addc_u32 s93, s93, 0
	s_add_u32 s36, s44, 0x34541000
	s_addc_u32 s37, s45, 0
	s_add_u32 s36, s36, s32
	s_addc_u32 s37, s37, 0
	global_load_dwordx4 v[140:143], v4, s[78:79]
	global_load_dwordx4 v[144:147], v4, s[78:79] offset:64
	global_load_dwordx4 v[148:151], v4, s[78:79] offset:128
	global_load_dwordx4 v[152:155], v4, s[78:79] offset:192
	global_load_dwordx4 v[156:159], v4, s[88:89]
	global_load_dwordx4 v[160:163], v4, s[88:89] offset:64
	global_load_dwordx4 v[164:167], v4, s[88:89] offset:128
	global_load_dwordx4 v[214:217], v4, s[88:89] offset:192
	global_load_dwordx4 v[16:19], v4, s[92:93]
	global_load_dwordx4 v[20:23], v4, s[92:93] offset:64
	global_load_dwordx4 v[24:27], v4, s[92:93] offset:128
	global_load_dwordx4 v[28:31], v4, s[92:93] offset:192
	global_load_dwordx4 v[182:185], v5, s[90:91]
	global_load_dwordx4 v[186:189], v5, s[90:91] offset:64
	global_load_dwordx4 v[190:193], v5, s[90:91] offset:128
	global_load_dwordx4 v[194:197], v5, s[90:91] offset:192
	global_load_dwordx4 v[198:201], v5, s[90:91] offset:256
	global_load_dwordx4 v[202:205], v5, s[90:91] offset:320
	global_load_dwordx4 v[206:209], v5, s[90:91] offset:384
	global_load_dwordx4 v[210:213], v5, s[90:91] offset:448
	s_waitcnt vmcnt(19)
	ds_write_b128 v6, v[140:143]
	s_waitcnt vmcnt(18)
	ds_write_b128 v6, v[144:147] offset:1024
	s_waitcnt vmcnt(17)
	ds_write_b128 v6, v[148:151] offset:2048
	s_waitcnt vmcnt(16)
	ds_write_b128 v6, v[152:155] offset:3072
	s_waitcnt vmcnt(15)
	ds_write_b128 v6, v[156:159] offset:4096
	s_waitcnt vmcnt(14)
	ds_write_b128 v6, v[160:163] offset:5120
	s_waitcnt vmcnt(13)
	ds_write_b128 v6, v[164:167] offset:6144
	s_waitcnt vmcnt(12)
	ds_write_b128 v6, v[214:217] offset:7168
	s_branch .Lma_staged

; __device__ __forceinline__ unsigned xb_add(unsigned* p, unsigned v) { return __hip_atomic_fetch_add(p, v, __ATOMIC_RELAXED, __HIP_MEMORY_SCOPE_AGENT); }
; __device__ __forceinline__ void xcd_barrier(const XcdBarrier& b) {
;     asm volatile("s_waitcnt vmcnt(0)" ::: "memory");
;     __syncthreads();
;     if (threadIdx.x == 0) {
;         unsigned* bar = b.bar;
;         __builtin_amdgcn_s_waitcnt(0);
;         unsigned nloc = b.st[0], nx = b.st[1];
;         if (nloc == 0u) { xcd_barrier_complete(bar, b.x, nloc, nx); b.st[0] = nloc; b.st[1] = nx; }
;         const unsigned old = xb_add(&bar[XB_XSUB(b.x)], 1u);
.LBB0_2406:
	s_setprio 0
	s_or_b64 exec, exec, s[6:7]
	s_waitcnt vmcnt(0)
	s_barrier
	s_and_saveexec_b64 s[6:7], s[86:87]
	s_cbranch_execz .LBB0_2458
	s_add_i32 s0, 0, 0x25fe0
	v_mov_b32_e32 v0, s0
	s_waitcnt vmcnt(0) expcnt(0) lgkmcnt(0)
	ds_read_b32 v2, v0
	s_add_i32 s0, 0, 0x25fe4
	v_mov_b32_e32 v0, s0
	ds_read_b32 v0, v0
	s_waitcnt lgkmcnt(1)
	v_cmp_ne_u32_e32 vcc, 0, v2
	s_cbranch_vccnz .LBB0_2422
	s_add_u32 s8, s44, 0x3ea4d200
	s_addc_u32 s9, s45, 0
	s_add_u32 s10, s44, 0x3ea4d400
	s_addc_u32 s11, s45, 0
	s_add_u32 s12, s44, 0x3ea4d500
	s_addc_u32 s13, s45, 0
	s_add_u32 s14, s44, 0x3ea4d600
	s_addc_u32 s15, s45, 0
	s_add_u32 s16, s44, 0x3ea4d700
	s_addc_u32 s17, s45, 0
	s_add_u32 s18, s44, 0x3ea4d800
	s_addc_u32 s19, s45, 0
	s_add_u32 s20, s44, 0x3ea4d900
	s_addc_u32 s21, s45, 0
	s_add_u32 s22, s44, 0x3ea4da00
	s_addc_u32 s23, s45, 0
	s_add_u32 s24, s44, 0x3ea4db00
	s_addc_u32 s25, s45, 0
	s_add_u32 s26, s44, 0x3ea4dc00
	s_addc_u32 s27, s45, 0
	s_add_u32 s28, s44, 0x3ea4dd00
	s_addc_u32 s29, s45, 0
	s_add_u32 s30, s44, 0x3ea4de00
	s_addc_u32 s31, s45, 0
	s_add_u32 s34, s44, 0x3ea4df00
	s_addc_u32 s35, s45, 0
	s_add_u32 s36, s44, 0x3ea4e000
	s_addc_u32 s37, s45, 0
	s_add_u32 s38, s44, 0x3ea4e100
	s_addc_u32 s39, s45, 0
	s_add_u32 s40, s44, 0x3ea4e200
	s_addc_u32 s41, s45, 0
	s_mul_i32 s0, s47, s84
	s_add_u32 s42, s44, 0x3ea4e300
	s_mul_i32 s0, s0, s46
	s_addc_u32 s43, s45, 0
	s_mov_b32 s1, 1
	v_mov_b32_e32 v16, 0
	s_branch .LBB0_2410
